# X50: X49 plus the phase-0 x->bf16 / row-sum loop hand-written with all 32 input pieces of a tile requested up front (prologue de-serialisation), re-tested with the paired measurement
# baseline (speedup 1.0000x reference)
; __device__ __forceinline__ unsigned lo_enc(float x, unsigned hb) { const float hf = __builtin_bit_cast(float, hb << 16); float t = (x - hf) * lo_inv(hb) + 128.0f; t = fminf(fmaxf(t, 1.0f), 255.0f); return (unsigned)__builtin_rintf(t); }
; __device__ __forceinline__ size_t lo_addr(int pm, int pn, int am, int wave, int lane) { return ((((size_t)(pm * 8 + pn) * 8 + am) * 8 + wave) * 64 + lane) * 16; }
; __device__ __forceinline__ unsigned pk2(float lo, float hi) { const f32x2_t v = {lo, hi}; return __builtin_bit_cast(unsigned, __builtin_convertvector(v, bf16x2_t)); }
; __device__ __forceinline__ void ph_prep(const float* x, bf16* xb, unsigned char* xlo, rs_t* rowss, int vcu, int G, int tid) {
;     const int lane = tid & 63, wave = tid >> 6, wr = wave >> 2, wc = wave & 3, fr = lane & 15, fq = lane >> 4;
;     for (int t = vcu; t < (M / 256) * (DM / 256); t += G) { const int pm = t >> 3, pn = t & 7;
; #pragma unroll
;         for (int am = 0; am < 8; ++am) { const int row = pm * 256 + (am >> 2) * 128 + wr * 64 + (am & 3) * 16 + fr; float ss = 0.f; v4u wl = {0u, 0u, 0u, 0u};
; #pragma unroll
;             for (int bj = 0; bj < 2; ++bj) { const size_t o2 = (size_t)row * DM + pn * 256 + bj * 128 + wc * 32 + 8 * fq; const f32x4 v0 = *(const f32x4*)(x + o2), v1 = *(const f32x4*)(x + o2 + 4);
;                 ss += (v0.x * v0.x + v0.y * v0.y) + (v0.z * v0.z + v0.w * v0.w) + (v1.x * v1.x + v1.y * v1.y) + (v1.z * v1.z + v1.w * v1.w);
;                 v4u w; w.x = pk2(v0.x, v0.y); w.y = pk2(v0.z, v0.w); w.z = pk2(v1.x, v1.y); w.w = pk2(v1.z, v1.w); *(v4u*)(xb + o2) = w;
;                 if (MK_LO) { wl[2 * bj] = pg8::lo_enc(v0.x, w.x & 0xffffu) | (pg8::lo_enc(v0.y, w.x >> 16) << 8) | (pg8::lo_enc(v0.z, w.y & 0xffffu) << 16) | (pg8::lo_enc(v0.w, w.y >> 16) << 24);
;                 wl[2 * bj + 1] = pg8::lo_enc(v1.x, w.z & 0xffffu) | (pg8::lo_enc(v1.y, w.z >> 16) << 8) | (pg8::lo_enc(v1.z, w.w & 0xffffu) << 16) | (pg8::lo_enc(v1.w, w.w >> 16) << 24); } }
;             if (MK_LO) *(v4u*)(xlo + pg8::lo_addr(pm, pn, am, wave, lane)) = wl;
;             ss += __shfl_xor(ss, 16); ss += __shfl_xor(ss, 32);
;             if (fq == 0) atomicAdd(rowss + row, (rs_t)(ss * RS_SCALE + 0.5f)); } }
; }
.LBB0_20:
	s_and_b32 s24, s28, 0xffffff00
	v_or_b32_e32 v2, s24, v6
	s_and_b32 s24, s26, 0x700
	v_or_b32_e32 v10, s24, v7
	v_readlane_b32 s36, v252, 5
	v_readlane_b32 s37, v252, 6
	v_lshl_add_u32 v3, v2, 11, v10
	v_lshlrev_b32_e32 v12, 2, v3
	v_lshlrev_b32_e32 v37, 2, v2
	v_add_u32_e32 v13, 0x20000, v12
	v_add_u32_e32 v14, 0x40000, v12
	v_add_u32_e32 v15, 0x60000, v12
	v_add_u32_e32 v16, 0x100000, v12
	v_add_u32_e32 v17, 0x120000, v12
	v_add_u32_e32 v18, 0x140000, v12
	v_add_u32_e32 v19, 0x160000, v12
	global_load_dwordx4 v[100:103], v12, s[36:37]
	global_load_dwordx4 v[104:107], v12, s[36:37] offset:16
	global_load_dwordx4 v[108:111], v12, s[36:37] offset:512
	global_load_dwordx4 v[112:115], v12, s[36:37] offset:528
	global_load_dwordx4 v[116:119], v13, s[36:37]
	global_load_dwordx4 v[120:123], v13, s[36:37] offset:16
	global_load_dwordx4 v[124:127], v13, s[36:37] offset:512
	global_load_dwordx4 v[128:131], v13, s[36:37] offset:528
	global_load_dwordx4 v[132:135], v14, s[36:37]
	global_load_dwordx4 v[136:139], v14, s[36:37] offset:16
	global_load_dwordx4 v[140:143], v14, s[36:37] offset:512
	global_load_dwordx4 v[144:147], v14, s[36:37] offset:528
	global_load_dwordx4 v[148:151], v15, s[36:37]
	global_load_dwordx4 v[152:155], v15, s[36:37] offset:16
	global_load_dwordx4 v[156:159], v15, s[36:37] offset:512
	global_load_dwordx4 v[160:163], v15, s[36:37] offset:528
	global_load_dwordx4 v[164:167], v16, s[36:37]
	global_load_dwordx4 v[168:171], v16, s[36:37] offset:16
	global_load_dwordx4 v[172:175], v16, s[36:37] offset:512
	global_load_dwordx4 v[176:179], v16, s[36:37] offset:528
	global_load_dwordx4 v[180:183], v17, s[36:37]
	global_load_dwordx4 v[184:187], v17, s[36:37] offset:16
	global_load_dwordx4 v[188:191], v17, s[36:37] offset:512
	global_load_dwordx4 v[192:195], v17, s[36:37] offset:528
	global_load_dwordx4 v[196:199], v18, s[36:37]
	global_load_dwordx4 v[200:203], v18, s[36:37] offset:16
	global_load_dwordx4 v[204:207], v18, s[36:37] offset:512
	global_load_dwordx4 v[208:211], v18, s[36:37] offset:528
	global_load_dwordx4 v[212:215], v19, s[36:37]
	global_load_dwordx4 v[216:219], v19, s[36:37] offset:16
	global_load_dwordx4 v[220:223], v19, s[36:37] offset:512
	global_load_dwordx4 v[224:227], v19, s[36:37] offset:528
	s_waitcnt vmcnt(28)
	v_mul_f32_e32 v20, v101, v101
	v_mul_f32_e32 v21, v103, v103
	v_mul_f32_e32 v22, v105, v105
	v_fmac_f32_e32 v20, v100, v100
	v_fmac_f32_e32 v21, v102, v102
	v_fmac_f32_e32 v22, v104, v104
	v_mul_f32_e32 v23, v107, v107
	v_add_f32_e32 v20, v20, v21
	v_fmac_f32_e32 v23, v106, v106
	v_add_f32_e32 v20, v20, v22
	v_add_f32_e32 v20, v23, v20
	v_cvt_pk_bf16_f32 v40, v100, v101
	v_cvt_pk_bf16_f32 v41, v102, v103
	v_cvt_pk_bf16_f32 v42, v104, v105
	v_cvt_pk_bf16_f32 v43, v106, v107
	v_mul_f32_e32 v24, v109, v109
	v_mul_f32_e32 v25, v111, v111
	v_mul_f32_e32 v26, v113, v113
	v_fmac_f32_e32 v24, v108, v108
	v_fmac_f32_e32 v25, v110, v110
	v_fmac_f32_e32 v26, v112, v112
	v_mul_f32_e32 v27, v115, v115
	v_add_f32_e32 v24, v24, v25
	v_fmac_f32_e32 v27, v114, v114
	v_add_f32_e32 v24, v24, v26
	v_add_f32_e32 v24, v27, v24
	v_cvt_pk_bf16_f32 v44, v108, v109
	v_cvt_pk_bf16_f32 v45, v110, v111
	v_cvt_pk_bf16_f32 v46, v112, v113
	v_cvt_pk_bf16_f32 v47, v114, v115
	v_add_f32_e32 v28, v20, v24
	v_lshrrev_b32_e32 v36, 1, v12
	global_store_dwordx4 v36, v[40:43], s[22:23]
	global_store_dwordx4 v36, v[44:47], s[22:23] offset:256
	s_waitcnt vmcnt(26)
	v_mul_f32_e32 v20, v117, v117
	v_mul_f32_e32 v21, v119, v119
	v_mul_f32_e32 v22, v121, v121
	v_fmac_f32_e32 v20, v116, v116
	v_fmac_f32_e32 v21, v118, v118
	v_fmac_f32_e32 v22, v120, v120
	v_mul_f32_e32 v23, v123, v123
	v_add_f32_e32 v20, v20, v21
	v_fmac_f32_e32 v23, v122, v122
	v_add_f32_e32 v20, v20, v22
	v_add_f32_e32 v20, v23, v20
	v_cvt_pk_bf16_f32 v40, v116, v117
	v_cvt_pk_bf16_f32 v41, v118, v119
	v_cvt_pk_bf16_f32 v42, v120, v121
	v_cvt_pk_bf16_f32 v43, v122, v123
	v_mul_f32_e32 v24, v125, v125
	v_mul_f32_e32 v25, v127, v127
	v_mul_f32_e32 v26, v129, v129
	v_fmac_f32_e32 v24, v124, v124
	v_fmac_f32_e32 v25, v126, v126
	v_fmac_f32_e32 v26, v128, v128
	v_mul_f32_e32 v27, v131, v131
	v_add_f32_e32 v24, v24, v25
	v_fmac_f32_e32 v27, v130, v130
	v_add_f32_e32 v24, v24, v26
	v_add_f32_e32 v24, v27, v24
	v_cvt_pk_bf16_f32 v44, v124, v125
	v_cvt_pk_bf16_f32 v45, v126, v127
	v_cvt_pk_bf16_f32 v46, v128, v129
	v_cvt_pk_bf16_f32 v47, v130, v131
	v_add_f32_e32 v29, v20, v24
	v_lshrrev_b32_e32 v36, 1, v13
	global_store_dwordx4 v36, v[40:43], s[22:23]
	global_store_dwordx4 v36, v[44:47], s[22:23] offset:256
	s_waitcnt vmcnt(24)
	v_mul_f32_e32 v20, v133, v133
	v_mul_f32_e32 v21, v135, v135
	v_mul_f32_e32 v22, v137, v137
	v_fmac_f32_e32 v20, v132, v132
	v_fmac_f32_e32 v21, v134, v134
	v_fmac_f32_e32 v22, v136, v136
	v_mul_f32_e32 v23, v139, v139
	v_add_f32_e32 v20, v20, v21
	v_fmac_f32_e32 v23, v138, v138
	v_add_f32_e32 v20, v20, v22
	v_add_f32_e32 v20, v23, v20
	v_cvt_pk_bf16_f32 v40, v132, v133
	v_cvt_pk_bf16_f32 v41, v134, v135
	v_cvt_pk_bf16_f32 v42, v136, v137
	v_cvt_pk_bf16_f32 v43, v138, v139
	v_mul_f32_e32 v24, v141, v141
	v_mul_f32_e32 v25, v143, v143
	v_mul_f32_e32 v26, v145, v145
	v_fmac_f32_e32 v24, v140, v140
	v_fmac_f32_e32 v25, v142, v142
	v_fmac_f32_e32 v26, v144, v144
	v_mul_f32_e32 v27, v147, v147
	v_add_f32_e32 v24, v24, v25
	v_fmac_f32_e32 v27, v146, v146
	v_add_f32_e32 v24, v24, v26
	v_add_f32_e32 v24, v27, v24
	v_cvt_pk_bf16_f32 v44, v140, v141
	v_cvt_pk_bf16_f32 v45, v142, v143
	v_cvt_pk_bf16_f32 v46, v144, v145
	v_cvt_pk_bf16_f32 v47, v146, v147
	v_add_f32_e32 v30, v20, v24
	v_lshrrev_b32_e32 v36, 1, v14
	global_store_dwordx4 v36, v[40:43], s[22:23]
	global_store_dwordx4 v36, v[44:47], s[22:23] offset:256
	s_waitcnt vmcnt(22)
; __device__ __forceinline__ unsigned lo_enc(float x, unsigned hb) { const float hf = __builtin_bit_cast(float, hb << 16); float t = (x - hf) * lo_inv(hb) + 128.0f; t = fminf(fmaxf(t, 1.0f), 255.0f); return (unsigned)__builtin_rintf(t); }
; __device__ __forceinline__ unsigned pk2(float lo, float hi) { const f32x2_t v = {lo, hi}; return __builtin_bit_cast(unsigned, __builtin_convertvector(v, bf16x2_t)); }
; __device__ __forceinline__ void ph_prep(const float* x, bf16* xb, unsigned char* xlo, rs_t* rowss, int vcu, int G, int tid) {
;     ...
;         for (int am = 0; am < 8; ++am) { const int row = pm * 256 + (am >> 2) * 128 + wr * 64 + (am & 3) * 16 + fr; float ss = 0.f; v4u wl = {0u, 0u, 0u, 0u};
; #pragma unroll
;             for (int bj = 0; bj < 2; ++bj) { const size_t o2 = (size_t)row * DM + pn * 256 + bj * 128 + wc * 32 + 8 * fq; const f32x4 v0 = *(const f32x4*)(x + o2), v1 = *(const f32x4*)(x + o2 + 4);
;                 ss += (v0.x * v0.x + v0.y * v0.y) + (v0.z * v0.z + v0.w * v0.w) + (v1.x * v1.x + v1.y * v1.y) + (v1.z * v1.z + v1.w * v1.w);
;                 v4u w; w.x = pk2(v0.x, v0.y); w.y = pk2(v0.z, v0.w); w.z = pk2(v1.x, v1.y); w.w = pk2(v1.z, v1.w); *(v4u*)(xb + o2) = w;
;                 if (MK_LO) { wl[2 * bj] = pg8::lo_enc(v0.x, w.x & 0xffffu) | (pg8::lo_enc(v0.y, w.x >> 16) << 8) | (pg8::lo_enc(v0.z, w.y & 0xffffu) << 16) | (pg8::lo_enc(v0.w, w.y >> 16) << 24);
;                 wl[2 * bj + 1] = pg8::lo_enc(v1.x, w.z & 0xffffu) | (pg8::lo_enc(v1.y, w.z >> 16) << 8) | (pg8::lo_enc(v1.z, w.w & 0xffffu) << 16) | (pg8::lo_enc(v1.w, w.w >> 16) << 24); } }
	v_mul_f32_e32 v20, v149, v149
	v_mul_f32_e32 v21, v151, v151
	v_mul_f32_e32 v22, v153, v153
	v_fmac_f32_e32 v20, v148, v148
	v_fmac_f32_e32 v21, v150, v150
	v_fmac_f32_e32 v22, v152, v152
	v_mul_f32_e32 v23, v155, v155
	v_add_f32_e32 v20, v20, v21
	v_fmac_f32_e32 v23, v154, v154
	v_add_f32_e32 v20, v20, v22
	v_add_f32_e32 v20, v23, v20
	v_cvt_pk_bf16_f32 v40, v148, v149
	v_cvt_pk_bf16_f32 v41, v150, v151
	v_cvt_pk_bf16_f32 v42, v152, v153
	v_cvt_pk_bf16_f32 v43, v154, v155
	v_mul_f32_e32 v24, v157, v157
	v_mul_f32_e32 v25, v159, v159
	v_mul_f32_e32 v26, v161, v161
	v_fmac_f32_e32 v24, v156, v156
	v_fmac_f32_e32 v25, v158, v158
	v_fmac_f32_e32 v26, v160, v160
	v_mul_f32_e32 v27, v163, v163
	v_add_f32_e32 v24, v24, v25
	v_fmac_f32_e32 v27, v162, v162
	v_add_f32_e32 v24, v24, v26
	v_add_f32_e32 v24, v27, v24
	v_cvt_pk_bf16_f32 v44, v156, v157
	v_cvt_pk_bf16_f32 v45, v158, v159
	v_cvt_pk_bf16_f32 v46, v160, v161
	v_cvt_pk_bf16_f32 v47, v162, v163
	v_add_f32_e32 v31, v20, v24
	v_lshrrev_b32_e32 v36, 1, v15
	global_store_dwordx4 v36, v[40:43], s[22:23]
	global_store_dwordx4 v36, v[44:47], s[22:23] offset:256
	s_waitcnt vmcnt(20)
	v_mul_f32_e32 v20, v165, v165
	v_mul_f32_e32 v21, v167, v167
	v_mul_f32_e32 v22, v169, v169
	v_fmac_f32_e32 v20, v164, v164
	v_fmac_f32_e32 v21, v166, v166
	v_fmac_f32_e32 v22, v168, v168
	v_mul_f32_e32 v23, v171, v171
	v_add_f32_e32 v20, v20, v21
	v_fmac_f32_e32 v23, v170, v170
	v_add_f32_e32 v20, v20, v22
	v_add_f32_e32 v20, v23, v20
	v_cvt_pk_bf16_f32 v40, v164, v165
	v_cvt_pk_bf16_f32 v41, v166, v167
	v_cvt_pk_bf16_f32 v42, v168, v169
	v_cvt_pk_bf16_f32 v43, v170, v171
	v_mul_f32_e32 v24, v173, v173
	v_mul_f32_e32 v25, v175, v175
	v_mul_f32_e32 v26, v177, v177
	v_fmac_f32_e32 v24, v172, v172
	v_fmac_f32_e32 v25, v174, v174
	v_fmac_f32_e32 v26, v176, v176
	v_mul_f32_e32 v27, v179, v179
	v_add_f32_e32 v24, v24, v25
	v_fmac_f32_e32 v27, v178, v178
	v_add_f32_e32 v24, v24, v26
	v_add_f32_e32 v24, v27, v24
	v_cvt_pk_bf16_f32 v44, v172, v173
	v_cvt_pk_bf16_f32 v45, v174, v175
	v_cvt_pk_bf16_f32 v46, v176, v177
	v_cvt_pk_bf16_f32 v47, v178, v179
	v_add_f32_e32 v32, v20, v24
	v_lshrrev_b32_e32 v36, 1, v16
	global_store_dwordx4 v36, v[40:43], s[22:23]
	global_store_dwordx4 v36, v[44:47], s[22:23] offset:256
	s_waitcnt vmcnt(18)
	v_mul_f32_e32 v20, v181, v181
	v_mul_f32_e32 v21, v183, v183
	v_mul_f32_e32 v22, v185, v185
	v_fmac_f32_e32 v20, v180, v180
	v_fmac_f32_e32 v21, v182, v182
	v_fmac_f32_e32 v22, v184, v184
	v_mul_f32_e32 v23, v187, v187
	v_add_f32_e32 v20, v20, v21
	v_fmac_f32_e32 v23, v186, v186
	v_add_f32_e32 v20, v20, v22
	v_add_f32_e32 v20, v23, v20
	v_cvt_pk_bf16_f32 v40, v180, v181
	v_cvt_pk_bf16_f32 v41, v182, v183
	v_cvt_pk_bf16_f32 v42, v184, v185
	v_cvt_pk_bf16_f32 v43, v186, v187
	v_mul_f32_e32 v24, v189, v189
	v_mul_f32_e32 v25, v191, v191
	v_mul_f32_e32 v26, v193, v193
	v_fmac_f32_e32 v24, v188, v188
	v_fmac_f32_e32 v25, v190, v190
	v_fmac_f32_e32 v26, v192, v192
	v_mul_f32_e32 v27, v195, v195
	v_add_f32_e32 v24, v24, v25
	v_fmac_f32_e32 v27, v194, v194
	v_add_f32_e32 v24, v24, v26
	v_add_f32_e32 v24, v27, v24
	v_cvt_pk_bf16_f32 v44, v188, v189
	v_cvt_pk_bf16_f32 v45, v190, v191
	v_cvt_pk_bf16_f32 v46, v192, v193
	v_cvt_pk_bf16_f32 v47, v194, v195
	v_add_f32_e32 v33, v20, v24
	v_lshrrev_b32_e32 v36, 1, v17
	global_store_dwordx4 v36, v[40:43], s[22:23]
	global_store_dwordx4 v36, v[44:47], s[22:23] offset:256
	s_waitcnt vmcnt(16)
; __device__ __forceinline__ unsigned lo_enc(float x, unsigned hb) { const float hf = __builtin_bit_cast(float, hb << 16); float t = (x - hf) * lo_inv(hb) + 128.0f; t = fminf(fmaxf(t, 1.0f), 255.0f); return (unsigned)__builtin_rintf(t); }
; __device__ __forceinline__ size_t lo_addr(int pm, int pn, int am, int wave, int lane) { return ((((size_t)(pm * 8 + pn) * 8 + am) * 8 + wave) * 64 + lane) * 16; }
; __device__ __forceinline__ unsigned pk2(float lo, float hi) { const f32x2_t v = {lo, hi}; return __builtin_bit_cast(unsigned, __builtin_convertvector(v, bf16x2_t)); }
; __device__ __forceinline__ void ph_prep(const float* x, bf16* xb, unsigned char* xlo, rs_t* rowss, int vcu, int G, int tid) {
;     ...
;         for (int am = 0; am < 8; ++am) { const int row = pm * 256 + (am >> 2) * 128 + wr * 64 + (am & 3) * 16 + fr; float ss = 0.f; v4u wl = {0u, 0u, 0u, 0u};
; #pragma unroll
;             for (int bj = 0; bj < 2; ++bj) { const size_t o2 = (size_t)row * DM + pn * 256 + bj * 128 + wc * 32 + 8 * fq; const f32x4 v0 = *(const f32x4*)(x + o2), v1 = *(const f32x4*)(x + o2 + 4);
;                 ss += (v0.x * v0.x + v0.y * v0.y) + (v0.z * v0.z + v0.w * v0.w) + (v1.x * v1.x + v1.y * v1.y) + (v1.z * v1.z + v1.w * v1.w);
;                 v4u w; w.x = pk2(v0.x, v0.y); w.y = pk2(v0.z, v0.w); w.z = pk2(v1.x, v1.y); w.w = pk2(v1.z, v1.w); *(v4u*)(xb + o2) = w;
;                 if (MK_LO) { wl[2 * bj] = pg8::lo_enc(v0.x, w.x & 0xffffu) | (pg8::lo_enc(v0.y, w.x >> 16) << 8) | (pg8::lo_enc(v0.z, w.y & 0xffffu) << 16) | (pg8::lo_enc(v0.w, w.y >> 16) << 24);
;                 wl[2 * bj + 1] = pg8::lo_enc(v1.x, w.z & 0xffffu) | (pg8::lo_enc(v1.y, w.z >> 16) << 8) | (pg8::lo_enc(v1.z, w.w & 0xffffu) << 16) | (pg8::lo_enc(v1.w, w.w >> 16) << 24); } }
;             if (MK_LO) *(v4u*)(xlo + pg8::lo_addr(pm, pn, am, wave, lane)) = wl;
;             ss += __shfl_xor(ss, 16); ss += __shfl_xor(ss, 32);
;             if (fq == 0) atomicAdd(rowss + row, (rs_t)(ss * RS_SCALE + 0.5f)); } }
	v_mul_f32_e32 v20, v197, v197
	v_mul_f32_e32 v21, v199, v199
	v_mul_f32_e32 v22, v201, v201
	v_fmac_f32_e32 v20, v196, v196
	v_fmac_f32_e32 v21, v198, v198
	v_fmac_f32_e32 v22, v200, v200
	v_mul_f32_e32 v23, v203, v203
	v_add_f32_e32 v20, v20, v21
	v_fmac_f32_e32 v23, v202, v202
	v_add_f32_e32 v20, v20, v22
	v_add_f32_e32 v20, v23, v20
	v_cvt_pk_bf16_f32 v40, v196, v197
	v_cvt_pk_bf16_f32 v41, v198, v199
	v_cvt_pk_bf16_f32 v42, v200, v201
	v_cvt_pk_bf16_f32 v43, v202, v203
	v_mul_f32_e32 v24, v205, v205
	v_mul_f32_e32 v25, v207, v207
	v_mul_f32_e32 v26, v209, v209
	v_fmac_f32_e32 v24, v204, v204
	v_fmac_f32_e32 v25, v206, v206
	v_fmac_f32_e32 v26, v208, v208
	v_mul_f32_e32 v27, v211, v211
	v_add_f32_e32 v24, v24, v25
	v_fmac_f32_e32 v27, v210, v210
	v_add_f32_e32 v24, v24, v26
	v_add_f32_e32 v24, v27, v24
	v_cvt_pk_bf16_f32 v44, v204, v205
	v_cvt_pk_bf16_f32 v45, v206, v207
	v_cvt_pk_bf16_f32 v46, v208, v209
	v_cvt_pk_bf16_f32 v47, v210, v211
	v_add_f32_e32 v34, v20, v24
	v_lshrrev_b32_e32 v36, 1, v18
	global_store_dwordx4 v36, v[40:43], s[22:23]
	global_store_dwordx4 v36, v[44:47], s[22:23] offset:256
	s_waitcnt vmcnt(14)
	v_mul_f32_e32 v20, v213, v213
	v_mul_f32_e32 v21, v215, v215
	v_mul_f32_e32 v22, v217, v217
	v_fmac_f32_e32 v20, v212, v212
	v_fmac_f32_e32 v21, v214, v214
	v_fmac_f32_e32 v22, v216, v216
	v_mul_f32_e32 v23, v219, v219
	v_add_f32_e32 v20, v20, v21
	v_fmac_f32_e32 v23, v218, v218
	v_add_f32_e32 v20, v20, v22
	v_add_f32_e32 v20, v23, v20
	v_cvt_pk_bf16_f32 v40, v212, v213
	v_cvt_pk_bf16_f32 v41, v214, v215
	v_cvt_pk_bf16_f32 v42, v216, v217
	v_cvt_pk_bf16_f32 v43, v218, v219
	v_mul_f32_e32 v24, v221, v221
	v_mul_f32_e32 v25, v223, v223
	v_mul_f32_e32 v26, v225, v225
	v_fmac_f32_e32 v24, v220, v220
	v_fmac_f32_e32 v25, v222, v222
	v_fmac_f32_e32 v26, v224, v224
	v_mul_f32_e32 v27, v227, v227
	v_add_f32_e32 v24, v24, v25
	v_fmac_f32_e32 v27, v226, v226
	v_add_f32_e32 v24, v24, v26
	v_add_f32_e32 v24, v27, v24
	v_cvt_pk_bf16_f32 v44, v220, v221
	v_cvt_pk_bf16_f32 v45, v222, v223
	v_cvt_pk_bf16_f32 v46, v224, v225
	v_cvt_pk_bf16_f32 v47, v226, v227
	v_add_f32_e32 v35, v20, v24
	v_lshrrev_b32_e32 v36, 1, v19
	global_store_dwordx4 v36, v[40:43], s[22:23]
	global_store_dwordx4 v36, v[44:47], s[22:23] offset:256
	ds_bpermute_b32 v48, v8, v28
	ds_bpermute_b32 v49, v8, v29
	ds_bpermute_b32 v50, v8, v30
	ds_bpermute_b32 v51, v8, v31
	ds_bpermute_b32 v52, v8, v32
	ds_bpermute_b32 v53, v8, v33
	ds_bpermute_b32 v54, v8, v34
	ds_bpermute_b32 v55, v8, v35
	s_waitcnt lgkmcnt(0)
	v_add_f32_e32 v28, v28, v48
	v_add_f32_e32 v29, v29, v49
	v_add_f32_e32 v30, v30, v50
	v_add_f32_e32 v31, v31, v51
	v_add_f32_e32 v32, v32, v52
	v_add_f32_e32 v33, v33, v53
	v_add_f32_e32 v34, v34, v54
	v_add_f32_e32 v35, v35, v55
	ds_bpermute_b32 v48, v9, v28
	ds_bpermute_b32 v49, v9, v29
	ds_bpermute_b32 v50, v9, v30
	ds_bpermute_b32 v51, v9, v31
	ds_bpermute_b32 v52, v9, v32
	ds_bpermute_b32 v53, v9, v33
	ds_bpermute_b32 v54, v9, v34
	ds_bpermute_b32 v55, v9, v35
	s_waitcnt lgkmcnt(0)
	v_add_f32_e32 v28, v28, v48
	v_add_f32_e32 v29, v29, v49
	v_add_f32_e32 v30, v30, v50
	v_add_f32_e32 v31, v31, v51
	v_add_f32_e32 v32, v32, v52
	v_add_f32_e32 v33, v33, v53
	v_add_f32_e32 v34, v34, v54
	v_add_f32_e32 v35, v35, v55
	v_fma_f32 v28, v28, s30, 0.5
	v_fma_f32 v29, v29, s30, 0.5
	v_fma_f32 v30, v30, s30, 0.5
	v_fma_f32 v31, v31, s30, 0.5
	v_fma_f32 v32, v32, s30, 0.5
	v_fma_f32 v33, v33, s30, 0.5
	v_fma_f32 v34, v34, s30, 0.5
	v_fma_f32 v35, v35, s30, 0.5
	v_cvt_u32_f32_e32 v28, v28
	v_cvt_u32_f32_e32 v29, v29
	v_cvt_u32_f32_e32 v30, v30
	v_cvt_u32_f32_e32 v31, v31
	v_cvt_u32_f32_e32 v32, v32
	v_cvt_u32_f32_e32 v33, v33
	v_cvt_u32_f32_e32 v34, v34
	v_cvt_u32_f32_e32 v35, v35
	s_and_saveexec_b64 s[24:25], vcc
	global_atomic_add v37, v28, s[0:1]
	global_atomic_add v37, v29, s[0:1] offset:64
	global_atomic_add v37, v30, s[0:1] offset:128
	global_atomic_add v37, v31, s[0:1] offset:192
	global_atomic_add v37, v32, s[0:1] offset:512
	global_atomic_add v37, v33, s[0:1] offset:576
	global_atomic_add v37, v34, s[0:1] offset:640
	global_atomic_add v37, v35, s[0:1] offset:704
	s_branch .LBB0_19
